# K-reversed GEMM loops: next-tile pointer selection computed branch-free in the previous MFMA segment tail instead of two branchy scalar blocks at the loop-top load segment
# baseline (speedup 1.0000x reference)
; #define PG8_STAGE(bufoff, gbase, voff) do { _Pragma("unroll") for (int _i = 0; _i < 2; ++_i) \
;         __builtin_amdgcn_global_load_lds((const unsigned*)((const char*)(gbase) + (voff)[_i]), (LAS unsigned*)(lds + (bufoff) + ldsw + _i * 8192), 16, 0, 0); } while (0)
; #define PG8_LDA(dst, b, h) do { _Pragma("unroll") for (int m = 0; m < 4; ++m) _Pragma("unroll") for (int k = 0; k < 2; ++k) dst[m][k] = *(const LAS bf16x8*)(lds + PG8_SA(b, h) + aoff + m * 2048 + k * 1024); } while (0)
; #define PG8_LDB(dst, b, h) do { _Pragma("unroll") for (int n = 0; n < 2; ++n) _Pragma("unroll") for (int k = 0; k < 2; ++k) dst[n][k] = *(const LAS bf16x8*)(lds + PG8_SB(b, h) + boff + n * 2048 + k * 1024); } while (0)
; #define PG8_MMA(ai, bj, At, Bt) do { __builtin_amdgcn_s_setprio(1); _Pragma("unroll") for (int m = 0; m < 4; ++m) _Pragma("unroll") for (int n = 0; n < 2; ++n) _Pragma("unroll") for (int k = 0; k < 2; ++k) \
;         acc[ai][bj][m][n] = __builtin_amdgcn_mfma_f32_16x16x32_bf16(Bt[n][k], At[m][k], acc[ai][bj][m][n], 0, 0, 0); __builtin_amdgcn_s_setprio(0); } while (0)
; #define PG8_WAIT_V(n) asm volatile("s_waitcnt vmcnt(" #n ")" ::: "memory")
; #define PG8_WAIT_L(n) asm volatile("s_waitcnt lgkmcnt(" #n ")" ::: "memory")
; #define PG8_BAR __builtin_amdgcn_s_barrier()
; #define PG8_SCHED __builtin_amdgcn_sched_barrier(0)
; template <class Epi, bool KREV = false>
; __device__ __forceinline__ void gemm_phase(LAS unsigned char* lds, const Gemm g, const StaticOrder& S, const Epi& E, int wave_s) {
;     ...
;             const char* a1 = cA + (size_t)(t + 1) * kstep;
;             const char* a2 = last ? nA : cA + (size_t)(t + 2) * kstep; const char* b2 = last ? nB : cB + (size_t)(t + 2) * kstep;
;             const char* a3 = a2 + kstep; const char* b3 = b2 + kstep;
;             PG8_LDB(B0, 0, 0); PG8_LDB(B1, 0, 1); PG8_SCHED; PG8_LDA(At, 0, 0); PG8_STAGE(PG8_SA(1, 1), a1 + hstep, voffA);
;             PG8_WAIT_V(8); PG8_WAIT_L(0); PG8_BAR; PG8_MMA(0, 0, At, B0); PG8_MMA(0, 1, At, B1); PG8_BAR; PG8_SCHED;
;             PG8_LDA(At, 0, 1); PG8_STAGE(PG8_SB(0, 0), b2, voffB); PG8_STAGE(PG8_SB(0, 1), b2 + bh, voffB); PG8_STAGE(PG8_SA(0, 0), a2, voffA);
;             PG8_WAIT_V(8); PG8_WAIT_L(0); PG8_BAR; PG8_MMA(1, 0, At, B0); PG8_MMA(1, 1, At, B1); PG8_BAR; PG8_SCHED;
.LBB0_640:
	s_or_b32 s80, s9, 1
	s_lshl_b64 s[46:47], s[80:81], 7
	s_sub_u32 s27, 0, s46
	s_subb_u32 s45, 0, s47
	s_add_i32 s48, 0, 0x10000
	s_add_i32 s49, 0, 0x14000
	s_add_u32 s46, s41, s27
	s_addc_u32 s47, s42, s45
	s_add_i32 m0, s34, 0xc000
	s_nop 0
	global_load_lds_dwordx4 v156, s[46:47]
	s_add_i32 m0, s34, 0xe000
	s_nop 0
	global_load_lds_dwordx4 v154, s[46:47]
	s_waitcnt vmcnt(8)
	s_waitcnt lgkmcnt(0)
	s_barrier
	s_setprio 1
	s_waitcnt lgkmcnt(0)
	v_mfma_f32_16x16x32_bf16 v[132:135], v[112:115], v[218:221], v[132:135]
	v_mfma_f32_16x16x32_bf16 v[120:123], v[136:139], v[218:221], v[120:123]
	v_mfma_f32_16x16x32_bf16 v[108:111], v[112:115], v[226:229], v[108:111]
	v_mfma_f32_16x16x32_bf16 v[104:107], v[136:139], v[226:229], v[104:107]
	v_mfma_f32_16x16x32_bf16 v[92:95], v[112:115], v[234:237], v[92:95]
	v_mfma_f32_16x16x32_bf16 v[88:91], v[136:139], v[234:237], v[88:91]
	v_mfma_f32_16x16x32_bf16 v[76:79], v[112:115], v[242:245], v[76:79]
	v_mfma_f32_16x16x32_bf16 v[72:75], v[136:139], v[242:245], v[72:75]
	v_mfma_f32_16x16x32_bf16 v[132:135], v[124:127], v[222:225], v[132:135]
	v_mfma_f32_16x16x32_bf16 v[120:123], v[140:143], v[222:225], v[120:123]
	v_mfma_f32_16x16x32_bf16 v[108:111], v[124:127], v[230:233], v[108:111]
	v_mfma_f32_16x16x32_bf16 v[104:107], v[140:143], v[230:233], v[104:107]
	v_mfma_f32_16x16x32_bf16 v[92:95], v[124:127], v[238:241], v[92:95]
	v_mfma_f32_16x16x32_bf16 v[88:91], v[140:143], v[238:241], v[88:91]
	v_mfma_f32_16x16x32_bf16 v[76:79], v[124:127], v[246:249], v[76:79]
	v_mfma_f32_16x16x32_bf16 v[72:75], v[140:143], v[246:249], v[72:75]
	s_setprio 0
	s_setprio 1
	v_mfma_f32_16x16x32_bf16 v[128:131], v[144:147], v[218:221], v[128:131]
	v_mfma_f32_16x16x32_bf16 v[116:119], v[194:197], v[218:221], v[116:119]
	v_mfma_f32_16x16x32_bf16 v[100:103], v[144:147], v[226:229], v[100:103]
	v_mfma_f32_16x16x32_bf16 v[96:99], v[194:197], v[226:229], v[96:99]
	v_mfma_f32_16x16x32_bf16 v[84:87], v[144:147], v[234:237], v[84:87]
	v_mfma_f32_16x16x32_bf16 v[80:83], v[194:197], v[234:237], v[80:83]
	v_mfma_f32_16x16x32_bf16 v[68:71], v[144:147], v[242:245], v[68:71]
	v_mfma_f32_16x16x32_bf16 v[64:67], v[194:197], v[242:245], v[64:67]
	v_mfma_f32_16x16x32_bf16 v[128:131], v[148:151], v[222:225], v[128:131]
	v_mfma_f32_16x16x32_bf16 v[116:119], v[202:205], v[222:225], v[116:119]
	v_mfma_f32_16x16x32_bf16 v[100:103], v[148:151], v[230:233], v[100:103]
	v_mfma_f32_16x16x32_bf16 v[96:99], v[202:205], v[230:233], v[96:99]
	v_mfma_f32_16x16x32_bf16 v[84:87], v[148:151], v[238:241], v[84:87]
	v_mfma_f32_16x16x32_bf16 v[80:83], v[202:205], v[238:241], v[80:83]
	v_mfma_f32_16x16x32_bf16 v[68:71], v[148:151], v[246:249], v[68:71]
	s_barrier
	v_mfma_f32_16x16x32_bf16 v[64:67], v[202:205], v[246:249], v[64:67]
	s_setprio 0
	s_add_u32 s98, s28, s78
	s_addc_u32 s99, s29, s79
	s_add_u32 s100, s30, s78
	s_addc_u32 s101, s31, s79
	s_add_i32 s27, s48, s1
	s_mov_b32 m0, s27
	ds_read_b128 v[218:221], v201 offset:16384
	ds_read_b128 v[222:225], v201 offset:17408
	ds_read_b128 v[226:229], v201 offset:18432
	ds_read_b128 v[230:233], v201 offset:19456
	ds_read_b128 v[234:237], v201 offset:20480
	ds_read_b128 v[238:241], v201 offset:21504
	ds_read_b128 v[242:245], v201 offset:22528
	ds_read_b128 v[246:249], v201 offset:23552
	global_load_lds_dwordx4 v176, s[28:29]
	s_add_i32 m0, s27, 0x2000
	s_add_u32 s46, s28, 0x80000
	s_addc_u32 s47, s29, 0
	s_add_i32 s27, s49, s1
	global_load_lds_dwordx4 v152, s[28:29]
	s_mov_b32 m0, s27
	s_nop 0
	global_load_lds_dwordx4 v176, s[46:47]
	s_add_i32 m0, s27, 0x2000
	s_nop 0
	global_load_lds_dwordx4 v152, s[46:47]
	s_mov_b32 m0, s34
	s_nop 0
	global_load_lds_dwordx4 v156, s[30:31]
	s_mov_b32 m0, s35
	s_nop 0
	global_load_lds_dwordx4 v154, s[30:31]
	s_waitcnt vmcnt(8)
	s_waitcnt lgkmcnt(0)
	s_barrier
	s_setprio 1
	s_waitcnt lgkmcnt(0)
	v_mfma_f32_16x16x32_bf16 v[60:63], v[112:115], v[218:221], v[60:63]
	v_mfma_f32_16x16x32_bf16 v[56:59], v[136:139], v[218:221], v[56:59]
	v_mfma_f32_16x16x32_bf16 v[44:47], v[112:115], v[226:229], v[44:47]
	v_mfma_f32_16x16x32_bf16 v[40:43], v[136:139], v[226:229], v[40:43]
	v_mfma_f32_16x16x32_bf16 v[28:31], v[112:115], v[234:237], v[28:31]
	v_mfma_f32_16x16x32_bf16 v[24:27], v[136:139], v[234:237], v[24:27]
	v_mfma_f32_16x16x32_bf16 v[12:15], v[112:115], v[242:245], v[12:15]
	v_mfma_f32_16x16x32_bf16 v[8:11], v[136:139], v[242:245], v[8:11]
	v_mfma_f32_16x16x32_bf16 v[60:63], v[124:127], v[222:225], v[60:63]
	v_mfma_f32_16x16x32_bf16 v[56:59], v[140:143], v[222:225], v[56:59]
	v_mfma_f32_16x16x32_bf16 v[44:47], v[124:127], v[230:233], v[44:47]
	v_mfma_f32_16x16x32_bf16 v[40:43], v[140:143], v[230:233], v[40:43]
	v_mfma_f32_16x16x32_bf16 v[28:31], v[124:127], v[238:241], v[28:31]
	v_mfma_f32_16x16x32_bf16 v[24:27], v[140:143], v[238:241], v[24:27]
	v_mfma_f32_16x16x32_bf16 v[12:15], v[124:127], v[246:249], v[12:15]
	v_mfma_f32_16x16x32_bf16 v[8:11], v[140:143], v[246:249], v[8:11]
	s_setprio 0
	s_setprio 1
	v_mfma_f32_16x16x32_bf16 v[52:55], v[144:147], v[218:221], v[52:55]
	v_mfma_f32_16x16x32_bf16 v[48:51], v[194:197], v[218:221], v[48:51]
	v_mfma_f32_16x16x32_bf16 v[36:39], v[144:147], v[226:229], v[36:39]
	v_mfma_f32_16x16x32_bf16 v[32:35], v[194:197], v[226:229], v[32:35]
	v_mfma_f32_16x16x32_bf16 v[20:23], v[144:147], v[234:237], v[20:23]
	v_mfma_f32_16x16x32_bf16 v[16:19], v[194:197], v[234:237], v[16:19]
	v_mfma_f32_16x16x32_bf16 v[4:7], v[144:147], v[242:245], v[4:7]
	v_mfma_f32_16x16x32_bf16 v[0:3], v[194:197], v[242:245], v[0:3]
	v_mfma_f32_16x16x32_bf16 v[52:55], v[148:151], v[222:225], v[52:55]
	v_mfma_f32_16x16x32_bf16 v[48:51], v[202:205], v[222:225], v[48:51]
	v_mfma_f32_16x16x32_bf16 v[36:39], v[148:151], v[230:233], v[36:39]
	v_mfma_f32_16x16x32_bf16 v[32:35], v[202:205], v[230:233], v[32:35]
	v_mfma_f32_16x16x32_bf16 v[20:23], v[148:151], v[238:241], v[20:23]
	v_mfma_f32_16x16x32_bf16 v[16:19], v[202:205], v[238:241], v[16:19]
	v_mfma_f32_16x16x32_bf16 v[4:7], v[148:151], v[246:249], v[4:7]
	s_barrier
; #define PG8_STAGE(bufoff, gbase, voff) do { _Pragma("unroll") for (int _i = 0; _i < 2; ++_i) \
;         __builtin_amdgcn_global_load_lds((const unsigned*)((const char*)(gbase) + (voff)[_i]), (LAS unsigned*)(lds + (bufoff) + ldsw + _i * 8192), 16, 0, 0); } while (0)
; #define PG8_LDA(dst, b, h) do { _Pragma("unroll") for (int m = 0; m < 4; ++m) _Pragma("unroll") for (int k = 0; k < 2; ++k) dst[m][k] = *(const LAS bf16x8*)(lds + PG8_SA(b, h) + aoff + m * 2048 + k * 1024); } while (0)
; #define PG8_LDB(dst, b, h) do { _Pragma("unroll") for (int n = 0; n < 2; ++n) _Pragma("unroll") for (int k = 0; k < 2; ++k) dst[n][k] = *(const LAS bf16x8*)(lds + PG8_SB(b, h) + boff + n * 2048 + k * 1024); } while (0)
; #define PG8_MMA(ai, bj, At, Bt) do { __builtin_amdgcn_s_setprio(1); _Pragma("unroll") for (int m = 0; m < 4; ++m) _Pragma("unroll") for (int n = 0; n < 2; ++n) _Pragma("unroll") for (int k = 0; k < 2; ++k) \
;         acc[ai][bj][m][n] = __builtin_amdgcn_mfma_f32_16x16x32_bf16(Bt[n][k], At[m][k], acc[ai][bj][m][n], 0, 0, 0); __builtin_amdgcn_s_setprio(0); } while (0)
; #define PG8_WAIT_V(n) asm volatile("s_waitcnt vmcnt(" #n ")" ::: "memory")
; #define PG8_WAIT_L(n) asm volatile("s_waitcnt lgkmcnt(" #n ")" ::: "memory")
; #define PG8_BAR __builtin_amdgcn_s_barrier()
; #define PG8_SCHED __builtin_amdgcn_sched_barrier(0)
; template <class Epi, bool KREV = false>
; __device__ __forceinline__ void gemm_phase(LAS unsigned char* lds, const Gemm g, const StaticOrder& S, const Epi& E, int wave_s) {
;     ...
;             PG8_LDB(B0, 1, 0); PG8_LDB(B1, 1, 1); PG8_SCHED; PG8_LDA(At, 1, 0); PG8_STAGE(PG8_SA(0, 1), a2 + hstep, voffA);
;             PG8_WAIT_V(8); PG8_WAIT_L(0); PG8_BAR; PG8_MMA(0, 0, At, B0); PG8_MMA(0, 1, At, B1); PG8_BAR; PG8_SCHED;
;             PG8_LDA(At, 1, 1); PG8_STAGE(PG8_SB(1, 0), b3, voffB); PG8_STAGE(PG8_SB(1, 1), b3 + bh, voffB); PG8_STAGE(PG8_SA(1, 0), a3, voffA);
	v_mfma_f32_16x16x32_bf16 v[0:3], v[202:205], v[246:249], v[0:3]
	s_setprio 0
	s_add_i32 s27, 0, 0x18000
	s_add_i32 s45, 0, 0x1c000
	v_add_u32_e32 v140, s27, v199
	v_add_u32_e32 v202, s45, v199
	ds_read_b128 v[112:115], v140
	ds_read_b128 v[124:127], v140 offset:1024
	ds_read_b128 v[136:139], v140 offset:2048
	ds_read_b128 v[140:143], v140 offset:3072
	ds_read_b128 v[144:147], v202
	ds_read_b128 v[148:151], v202 offset:1024
	ds_read_b128 v[194:197], v202 offset:2048
	ds_read_b128 v[202:205], v202 offset:3072
	s_add_u32 s30, s30, 0x80000
	s_addc_u32 s31, s31, 0
	s_mov_b32 m0, s36
	ds_read_b128 v[218:221], v201 offset:32768
	ds_read_b128 v[222:225], v201 offset:33792
	ds_read_b128 v[226:229], v201 offset:34816
	ds_read_b128 v[230:233], v201 offset:35840
	ds_read_b128 v[234:237], v201 offset:36864
	ds_read_b128 v[238:241], v201 offset:37888
	ds_read_b128 v[242:245], v201 offset:38912
	ds_read_b128 v[246:249], v201 offset:39936
	global_load_lds_dwordx4 v156, s[30:31]
	s_mov_b32 m0, s37
	s_nop 0
	global_load_lds_dwordx4 v154, s[30:31]
	s_waitcnt vmcnt(8)
	s_waitcnt lgkmcnt(0)
	s_barrier
	s_setprio 1
	s_waitcnt lgkmcnt(0)
	v_mfma_f32_16x16x32_bf16 v[132:135], v[112:115], v[218:221], v[132:135]
	v_mfma_f32_16x16x32_bf16 v[120:123], v[136:139], v[218:221], v[120:123]
	v_mfma_f32_16x16x32_bf16 v[108:111], v[112:115], v[226:229], v[108:111]
	v_mfma_f32_16x16x32_bf16 v[104:107], v[136:139], v[226:229], v[104:107]
	v_mfma_f32_16x16x32_bf16 v[92:95], v[112:115], v[234:237], v[92:95]
	v_mfma_f32_16x16x32_bf16 v[88:91], v[136:139], v[234:237], v[88:91]
	v_mfma_f32_16x16x32_bf16 v[76:79], v[112:115], v[242:245], v[76:79]
	v_mfma_f32_16x16x32_bf16 v[72:75], v[136:139], v[242:245], v[72:75]
	v_mfma_f32_16x16x32_bf16 v[132:135], v[124:127], v[222:225], v[132:135]
	v_mfma_f32_16x16x32_bf16 v[120:123], v[140:143], v[222:225], v[120:123]
	v_mfma_f32_16x16x32_bf16 v[108:111], v[124:127], v[230:233], v[108:111]
	v_mfma_f32_16x16x32_bf16 v[104:107], v[140:143], v[230:233], v[104:107]
	v_mfma_f32_16x16x32_bf16 v[92:95], v[124:127], v[238:241], v[92:95]
	v_mfma_f32_16x16x32_bf16 v[88:91], v[140:143], v[238:241], v[88:91]
	v_mfma_f32_16x16x32_bf16 v[76:79], v[124:127], v[246:249], v[76:79]
	v_mfma_f32_16x16x32_bf16 v[72:75], v[140:143], v[246:249], v[72:75]
	s_setprio 0
	s_setprio 1
	v_mfma_f32_16x16x32_bf16 v[128:131], v[144:147], v[218:221], v[128:131]
	v_mfma_f32_16x16x32_bf16 v[116:119], v[194:197], v[218:221], v[116:119]
	v_mfma_f32_16x16x32_bf16 v[100:103], v[144:147], v[226:229], v[100:103]
	v_mfma_f32_16x16x32_bf16 v[96:99], v[194:197], v[226:229], v[96:99]
	v_mfma_f32_16x16x32_bf16 v[84:87], v[144:147], v[234:237], v[84:87]
	v_mfma_f32_16x16x32_bf16 v[80:83], v[194:197], v[234:237], v[80:83]
	v_mfma_f32_16x16x32_bf16 v[68:71], v[144:147], v[242:245], v[68:71]
	v_mfma_f32_16x16x32_bf16 v[64:67], v[194:197], v[242:245], v[64:67]
	v_mfma_f32_16x16x32_bf16 v[128:131], v[148:151], v[222:225], v[128:131]
	v_mfma_f32_16x16x32_bf16 v[116:119], v[202:205], v[222:225], v[116:119]
	v_mfma_f32_16x16x32_bf16 v[100:103], v[148:151], v[230:233], v[100:103]
	v_mfma_f32_16x16x32_bf16 v[96:99], v[202:205], v[230:233], v[96:99]
	v_mfma_f32_16x16x32_bf16 v[84:87], v[148:151], v[238:241], v[84:87]
	v_mfma_f32_16x16x32_bf16 v[80:83], v[202:205], v[238:241], v[80:83]
	v_mfma_f32_16x16x32_bf16 v[68:71], v[148:151], v[246:249], v[68:71]
	s_barrier
	v_mfma_f32_16x16x32_bf16 v[64:67], v[202:205], v[246:249], v[64:67]
	s_setprio 0
	s_add_i32 s27, s27, s1
	s_mov_b32 m0, s27
	ds_read_b128 v[218:221], v201 offset:49152
	ds_read_b128 v[222:225], v201 offset:50176
	ds_read_b128 v[226:229], v201 offset:51200
	ds_read_b128 v[230:233], v201 offset:52224
	ds_read_b128 v[234:237], v201 offset:53248
	ds_read_b128 v[238:241], v201 offset:54272
	ds_read_b128 v[242:245], v201 offset:55296
	ds_read_b128 v[246:249], v201 offset:56320
	global_load_lds_dwordx4 v176, s[98:99]
	s_add_i32 m0, s27, 0x2000
	s_add_u32 s28, s28, 0x7ff80
	s_addc_u32 s29, s29, 0
	s_add_i32 s27, s45, s1
	global_load_lds_dwordx4 v152, s[98:99]
	s_mov_b32 m0, s27
	s_nop 0
	global_load_lds_dwordx4 v176, s[28:29]
	s_add_i32 m0, s27, 0x2000
	s_nop 0
	global_load_lds_dwordx4 v152, s[28:29]
	s_mov_b32 m0, s39
	s_nop 0
	global_load_lds_dwordx4 v156, s[100:101]
	s_mov_b32 m0, s40
	s_nop 0
	global_load_lds_dwordx4 v154, s[100:101]
	s_waitcnt vmcnt(8)
	s_waitcnt lgkmcnt(0)
	s_barrier
; #define PG8_STAGE(bufoff, gbase, voff) do { _Pragma("unroll") for (int _i = 0; _i < 2; ++_i) \
;         __builtin_amdgcn_global_load_lds((const unsigned*)((const char*)(gbase) + (voff)[_i]), (LAS unsigned*)(lds + (bufoff) + ldsw + _i * 8192), 16, 0, 0); } while (0)
; #define PG8_LDA(dst, b, h) do { _Pragma("unroll") for (int m = 0; m < 4; ++m) _Pragma("unroll") for (int k = 0; k < 2; ++k) dst[m][k] = *(const LAS bf16x8*)(lds + PG8_SA(b, h) + aoff + m * 2048 + k * 1024); } while (0)
; #define PG8_LDB(dst, b, h) do { _Pragma("unroll") for (int n = 0; n < 2; ++n) _Pragma("unroll") for (int k = 0; k < 2; ++k) dst[n][k] = *(const LAS bf16x8*)(lds + PG8_SB(b, h) + boff + n * 2048 + k * 1024); } while (0)
; #define PG8_MMA(ai, bj, At, Bt) do { __builtin_amdgcn_s_setprio(1); _Pragma("unroll") for (int m = 0; m < 4; ++m) _Pragma("unroll") for (int n = 0; n < 2; ++n) _Pragma("unroll") for (int k = 0; k < 2; ++k) \
;         acc[ai][bj][m][n] = __builtin_amdgcn_mfma_f32_16x16x32_bf16(Bt[n][k], At[m][k], acc[ai][bj][m][n], 0, 0, 0); __builtin_amdgcn_s_setprio(0); } while (0)
; #define PG8_WAIT_V(n) asm volatile("s_waitcnt vmcnt(" #n ")" ::: "memory")
; #define PG8_WAIT_L(n) asm volatile("s_waitcnt lgkmcnt(" #n ")" ::: "memory")
; #define PG8_BAR __builtin_amdgcn_s_barrier()
; #define PG8_SCHED __builtin_amdgcn_sched_barrier(0)
; template <class Epi, bool KREV = false>
; __device__ __forceinline__ void gemm_phase(LAS unsigned char* lds, const Gemm g, const StaticOrder& S, const Epi& E, int wave_s) {
;     ...
;         const bool has_next = S.next(ui + 1, nxt);
;         const char* nA = has_next ? (const char*)g.A + (size_t)nxt.pm * tstep + k0off : cA; const char* nB = has_next ? (const char*)g.Bt + (size_t)nxt.pn * bunit + k0off : cB;
;         for (int t = 0; t < nt; t += 2) {
;             const bool last = (t == nt - 2);
;             const char* a1 = cA + (size_t)(t + 1) * kstep;
;             const char* a2 = last ? nA : cA + (size_t)(t + 2) * kstep; const char* b2 = last ? nB : cB + (size_t)(t + 2) * kstep;
;             const char* a3 = a2 + kstep; const char* b3 = b2 + kstep;
;             PG8_LDB(B0, 0, 0); PG8_LDB(B1, 0, 1); PG8_SCHED; PG8_LDA(At, 0, 0); PG8_STAGE(PG8_SA(1, 1), a1 + hstep, voffA);
;     ...
;             PG8_WAIT_V(8); PG8_WAIT_L(0); PG8_BAR; PG8_MMA(1, 0, At, B0); PG8_MMA(1, 1, At, B1); PG8_BAR; PG8_SCHED;
;         }
	s_setprio 1
	s_waitcnt lgkmcnt(0)
	v_mfma_f32_16x16x32_bf16 v[60:63], v[112:115], v[218:221], v[60:63]
	v_mfma_f32_16x16x32_bf16 v[56:59], v[136:139], v[218:221], v[56:59]
	v_mfma_f32_16x16x32_bf16 v[44:47], v[112:115], v[226:229], v[44:47]
	v_mfma_f32_16x16x32_bf16 v[40:43], v[136:139], v[226:229], v[40:43]
	v_mfma_f32_16x16x32_bf16 v[28:31], v[112:115], v[234:237], v[28:31]
	v_mfma_f32_16x16x32_bf16 v[24:27], v[136:139], v[234:237], v[24:27]
	v_mfma_f32_16x16x32_bf16 v[12:15], v[112:115], v[242:245], v[12:15]
	v_mfma_f32_16x16x32_bf16 v[8:11], v[136:139], v[242:245], v[8:11]
	v_mfma_f32_16x16x32_bf16 v[60:63], v[124:127], v[222:225], v[60:63]
	v_mfma_f32_16x16x32_bf16 v[56:59], v[140:143], v[222:225], v[56:59]
	v_mfma_f32_16x16x32_bf16 v[44:47], v[124:127], v[230:233], v[44:47]
	v_mfma_f32_16x16x32_bf16 v[40:43], v[140:143], v[230:233], v[40:43]
	v_mfma_f32_16x16x32_bf16 v[28:31], v[124:127], v[238:241], v[28:31]
	v_mfma_f32_16x16x32_bf16 v[24:27], v[140:143], v[238:241], v[24:27]
	v_mfma_f32_16x16x32_bf16 v[12:15], v[124:127], v[246:249], v[12:15]
	v_mfma_f32_16x16x32_bf16 v[8:11], v[140:143], v[246:249], v[8:11]
	s_setprio 0
	s_setprio 1
	v_mfma_f32_16x16x32_bf16 v[52:55], v[144:147], v[218:221], v[52:55]
	v_mfma_f32_16x16x32_bf16 v[48:51], v[194:197], v[218:221], v[48:51]
	v_mfma_f32_16x16x32_bf16 v[36:39], v[144:147], v[226:229], v[36:39]
	v_mfma_f32_16x16x32_bf16 v[32:35], v[194:197], v[226:229], v[32:35]
	v_mfma_f32_16x16x32_bf16 v[20:23], v[144:147], v[234:237], v[20:23]
	v_mfma_f32_16x16x32_bf16 v[16:19], v[194:197], v[234:237], v[16:19]
	v_mfma_f32_16x16x32_bf16 v[4:7], v[144:147], v[242:245], v[4:7]
	v_mfma_f32_16x16x32_bf16 v[0:3], v[194:197], v[242:245], v[0:3]
	s_cmp_gt_u32 s9, 29
	s_cselect_b32 s32, 1, 0
	s_mov_b32 s9, s26
	v_mfma_f32_16x16x32_bf16 v[52:55], v[148:151], v[222:225], v[52:55]
	s_add_i32 s80, s9, 2
	s_lshl_b32 vcc_lo, s80, 7
	v_mfma_f32_16x16x32_bf16 v[48:51], v[202:205], v[222:225], v[48:51]
	s_sub_u32 s30, s12, vcc_lo
	s_subb_u32 s31, s13, 0
	v_mfma_f32_16x16x32_bf16 v[36:39], v[148:151], v[230:233], v[36:39]
	s_sub_u32 s28, s22, vcc_lo
	s_subb_u32 s29, s23, 0
	v_mfma_f32_16x16x32_bf16 v[32:35], v[202:205], v[230:233], v[32:35]
	s_cmp_eq_u32 s9, 30
	s_cselect_b32 s30, s12, s30
	s_cselect_b32 s31, s13, s31
	v_mfma_f32_16x16x32_bf16 v[20:23], v[148:151], v[238:241], v[20:23]
	s_cselect_b32 s28, s24, s28
	s_cselect_b32 s29, s25, s29
	s_cselect_b32 s26, 32, s80
	v_mfma_f32_16x16x32_bf16 v[16:19], v[202:205], v[238:241], v[16:19]
	s_cmp_lg_u32 s32, 0
	v_mfma_f32_16x16x32_bf16 v[4:7], v[148:151], v[246:249], v[4:7]
	s_barrier
	v_mfma_f32_16x16x32_bf16 v[0:3], v[202:205], v[246:249], v[0:3]
	s_setprio 0
	s_cbranch_scc1 .LBB0_645
	v_add_u32_e32 v140, 0x10000, v199
	v_add_u32_e32 v202, 0x14000, v199
	ds_read_b128 v[112:115], v140
	ds_read_b128 v[124:127], v140 offset:1024
	ds_read_b128 v[136:139], v140 offset:2048
	ds_read_b128 v[140:143], v140 offset:3072
	ds_read_b128 v[144:147], v202
	ds_read_b128 v[148:151], v202 offset:1024
	ds_read_b128 v[194:197], v202 offset:2048
	ds_read_b128 v[202:205], v202 offset:3072
	ds_read_b128 v[218:221], v201
	ds_read_b128 v[222:225], v201 offset:1024
	ds_read_b128 v[226:229], v201 offset:2048
	ds_read_b128 v[230:233], v201 offset:3072
	ds_read_b128 v[234:237], v201 offset:4096
	ds_read_b128 v[238:241], v201 offset:5120
	ds_read_b128 v[242:245], v201 offset:6144
	ds_read_b128 v[246:249], v201 offset:7168
	s_branch .LBB0_640

; #define PG8_STAGE(bufoff, gbase, voff) do { _Pragma("unroll") for (int _i = 0; _i < 2; ++_i) \
;         __builtin_amdgcn_global_load_lds((const unsigned*)((const char*)(gbase) + (voff)[_i]), (LAS unsigned*)(lds + (bufoff) + ldsw + _i * 8192), 16, 0, 0); } while (0)
; #define PG8_LDA(dst, b, h) do { _Pragma("unroll") for (int m = 0; m < 4; ++m) _Pragma("unroll") for (int k = 0; k < 2; ++k) dst[m][k] = *(const LAS bf16x8*)(lds + PG8_SA(b, h) + aoff + m * 2048 + k * 1024); } while (0)
; #define PG8_LDB(dst, b, h) do { _Pragma("unroll") for (int n = 0; n < 2; ++n) _Pragma("unroll") for (int k = 0; k < 2; ++k) dst[n][k] = *(const LAS bf16x8*)(lds + PG8_SB(b, h) + boff + n * 2048 + k * 1024); } while (0)
; #define PG8_MMA(ai, bj, At, Bt) do { __builtin_amdgcn_s_setprio(1); _Pragma("unroll") for (int m = 0; m < 4; ++m) _Pragma("unroll") for (int n = 0; n < 2; ++n) _Pragma("unroll") for (int k = 0; k < 2; ++k) \
;         acc[ai][bj][m][n] = __builtin_amdgcn_mfma_f32_16x16x32_bf16(Bt[n][k], At[m][k], acc[ai][bj][m][n], 0, 0, 0); __builtin_amdgcn_s_setprio(0); } while (0)
; #define PG8_WAIT_V(n) asm volatile("s_waitcnt vmcnt(" #n ")" ::: "memory")
; #define PG8_WAIT_L(n) asm volatile("s_waitcnt lgkmcnt(" #n ")" ::: "memory")
; #define PG8_BAR __builtin_amdgcn_s_barrier()
; #define PG8_SCHED __builtin_amdgcn_sched_barrier(0)
; template <class Epi, bool KREV = false>
; __device__ __forceinline__ void gemm_phase(LAS unsigned char* lds, const Gemm g, const StaticOrder& S, const Epi& E, int wave_s) {
;     ...
;             const char* a1 = cA + (size_t)(t + 1) * kstep;
;             const char* a2 = last ? nA : cA + (size_t)(t + 2) * kstep; const char* b2 = last ? nB : cB + (size_t)(t + 2) * kstep;
;             const char* a3 = a2 + kstep; const char* b3 = b2 + kstep;
;             PG8_LDB(B0, 0, 0); PG8_LDB(B1, 0, 1); PG8_SCHED; PG8_LDA(At, 0, 0); PG8_STAGE(PG8_SA(1, 1), a1 + hstep, voffA);
;             PG8_WAIT_V(8); PG8_WAIT_L(0); PG8_BAR; PG8_MMA(0, 0, At, B0); PG8_MMA(0, 1, At, B1); PG8_BAR; PG8_SCHED;
;             PG8_LDA(At, 0, 1); PG8_STAGE(PG8_SB(0, 0), b2, voffB); PG8_STAGE(PG8_SB(0, 1), b2 + bh, voffB); PG8_STAGE(PG8_SA(0, 0), a2, voffA);
;             PG8_WAIT_V(8); PG8_WAIT_L(0); PG8_BAR; PG8_MMA(1, 0, At, B0); PG8_MMA(1, 1, At, B1); PG8_BAR; PG8_SCHED;
.LBB0_1023:
	s_or_b32 s80, s44, 1
	s_lshl_b64 s[46:47], s[80:81], 7
	s_sub_u32 s23, 0, s46
	s_subb_u32 s45, 0, s47
	s_add_i32 s48, 0, 0x10000
	s_add_i32 s49, 0, 0x14000
	s_add_u32 s46, s42, s23
	s_addc_u32 s47, s43, s45
	s_add_i32 m0, s28, 0xc000
	s_nop 0
	global_load_lds_dwordx4 v156, s[46:47]
	s_add_i32 m0, s28, 0xe000
	s_nop 0
	global_load_lds_dwordx4 v154, s[46:47]
	s_waitcnt vmcnt(8)
	s_waitcnt lgkmcnt(0)
	s_barrier
	s_setprio 1
	s_waitcnt lgkmcnt(0)
	v_mfma_f32_16x16x32_bf16 v[132:135], v[112:115], v[218:221], v[132:135]
	v_mfma_f32_16x16x32_bf16 v[120:123], v[136:139], v[218:221], v[120:123]
	v_mfma_f32_16x16x32_bf16 v[108:111], v[112:115], v[226:229], v[108:111]
	v_mfma_f32_16x16x32_bf16 v[104:107], v[136:139], v[226:229], v[104:107]
	v_mfma_f32_16x16x32_bf16 v[92:95], v[112:115], v[234:237], v[92:95]
	v_mfma_f32_16x16x32_bf16 v[88:91], v[136:139], v[234:237], v[88:91]
	v_mfma_f32_16x16x32_bf16 v[76:79], v[112:115], v[242:245], v[76:79]
	v_mfma_f32_16x16x32_bf16 v[72:75], v[136:139], v[242:245], v[72:75]
	v_mfma_f32_16x16x32_bf16 v[132:135], v[124:127], v[222:225], v[132:135]
	v_mfma_f32_16x16x32_bf16 v[120:123], v[140:143], v[222:225], v[120:123]
	v_mfma_f32_16x16x32_bf16 v[108:111], v[124:127], v[230:233], v[108:111]
	v_mfma_f32_16x16x32_bf16 v[104:107], v[140:143], v[230:233], v[104:107]
	v_mfma_f32_16x16x32_bf16 v[92:95], v[124:127], v[238:241], v[92:95]
	v_mfma_f32_16x16x32_bf16 v[88:91], v[140:143], v[238:241], v[88:91]
	v_mfma_f32_16x16x32_bf16 v[76:79], v[124:127], v[246:249], v[76:79]
	v_mfma_f32_16x16x32_bf16 v[72:75], v[140:143], v[246:249], v[72:75]
	s_setprio 0
	s_setprio 1
	v_mfma_f32_16x16x32_bf16 v[128:131], v[144:147], v[218:221], v[128:131]
	v_mfma_f32_16x16x32_bf16 v[116:119], v[194:197], v[218:221], v[116:119]
	v_mfma_f32_16x16x32_bf16 v[100:103], v[144:147], v[226:229], v[100:103]
	v_mfma_f32_16x16x32_bf16 v[96:99], v[194:197], v[226:229], v[96:99]
	v_mfma_f32_16x16x32_bf16 v[84:87], v[144:147], v[234:237], v[84:87]
	v_mfma_f32_16x16x32_bf16 v[80:83], v[194:197], v[234:237], v[80:83]
	v_mfma_f32_16x16x32_bf16 v[68:71], v[144:147], v[242:245], v[68:71]
	v_mfma_f32_16x16x32_bf16 v[64:67], v[194:197], v[242:245], v[64:67]
	v_mfma_f32_16x16x32_bf16 v[128:131], v[148:151], v[222:225], v[128:131]
	v_mfma_f32_16x16x32_bf16 v[116:119], v[202:205], v[222:225], v[116:119]
	v_mfma_f32_16x16x32_bf16 v[100:103], v[148:151], v[230:233], v[100:103]
	v_mfma_f32_16x16x32_bf16 v[96:99], v[202:205], v[230:233], v[96:99]
	v_mfma_f32_16x16x32_bf16 v[84:87], v[148:151], v[238:241], v[84:87]
	v_mfma_f32_16x16x32_bf16 v[80:83], v[202:205], v[238:241], v[80:83]
	v_mfma_f32_16x16x32_bf16 v[68:71], v[148:151], v[246:249], v[68:71]
	s_barrier
	v_mfma_f32_16x16x32_bf16 v[64:67], v[202:205], v[246:249], v[64:67]
	s_setprio 0
	s_add_u32 s98, s24, s78
	s_addc_u32 s99, s25, s79
	s_add_u32 s100, s26, s78
	s_addc_u32 s101, s27, s79
	s_add_i32 s23, s48, s1
	s_mov_b32 m0, s23
	ds_read_b128 v[218:221], v201 offset:16384
	ds_read_b128 v[222:225], v201 offset:17408
	ds_read_b128 v[226:229], v201 offset:18432
	ds_read_b128 v[230:233], v201 offset:19456
	ds_read_b128 v[234:237], v201 offset:20480
	ds_read_b128 v[238:241], v201 offset:21504
	ds_read_b128 v[242:245], v201 offset:22528
	ds_read_b128 v[246:249], v201 offset:23552
	global_load_lds_dwordx4 v176, s[24:25]
	s_add_i32 m0, s23, 0x2000
	s_add_u32 s46, s24, 0x160000
	s_addc_u32 s47, s25, 0
	s_add_i32 s23, s49, s1
	global_load_lds_dwordx4 v152, s[24:25]
	s_mov_b32 m0, s23
	s_nop 0
	global_load_lds_dwordx4 v176, s[46:47]
	s_add_i32 m0, s23, 0x2000
	s_nop 0
	global_load_lds_dwordx4 v152, s[46:47]
	s_mov_b32 m0, s28
	s_nop 0
	global_load_lds_dwordx4 v156, s[26:27]
	s_mov_b32 m0, s29
	s_nop 0
	global_load_lds_dwordx4 v154, s[26:27]
	s_waitcnt vmcnt(8)
	s_waitcnt lgkmcnt(0)
	s_barrier
	s_setprio 1
	s_waitcnt lgkmcnt(0)
	v_mfma_f32_16x16x32_bf16 v[60:63], v[112:115], v[218:221], v[60:63]
	v_mfma_f32_16x16x32_bf16 v[56:59], v[136:139], v[218:221], v[56:59]
	v_mfma_f32_16x16x32_bf16 v[44:47], v[112:115], v[226:229], v[44:47]
	v_mfma_f32_16x16x32_bf16 v[40:43], v[136:139], v[226:229], v[40:43]
	v_mfma_f32_16x16x32_bf16 v[28:31], v[112:115], v[234:237], v[28:31]
	v_mfma_f32_16x16x32_bf16 v[24:27], v[136:139], v[234:237], v[24:27]
	v_mfma_f32_16x16x32_bf16 v[12:15], v[112:115], v[242:245], v[12:15]
	v_mfma_f32_16x16x32_bf16 v[8:11], v[136:139], v[242:245], v[8:11]
	v_mfma_f32_16x16x32_bf16 v[60:63], v[124:127], v[222:225], v[60:63]
	v_mfma_f32_16x16x32_bf16 v[56:59], v[140:143], v[222:225], v[56:59]
	v_mfma_f32_16x16x32_bf16 v[44:47], v[124:127], v[230:233], v[44:47]
	v_mfma_f32_16x16x32_bf16 v[40:43], v[140:143], v[230:233], v[40:43]
	v_mfma_f32_16x16x32_bf16 v[28:31], v[124:127], v[238:241], v[28:31]
	v_mfma_f32_16x16x32_bf16 v[24:27], v[140:143], v[238:241], v[24:27]
	v_mfma_f32_16x16x32_bf16 v[12:15], v[124:127], v[246:249], v[12:15]
	v_mfma_f32_16x16x32_bf16 v[8:11], v[140:143], v[246:249], v[8:11]
	s_setprio 0
	s_setprio 1
	v_mfma_f32_16x16x32_bf16 v[52:55], v[144:147], v[218:221], v[52:55]
	v_mfma_f32_16x16x32_bf16 v[48:51], v[194:197], v[218:221], v[48:51]
	v_mfma_f32_16x16x32_bf16 v[36:39], v[144:147], v[226:229], v[36:39]
	v_mfma_f32_16x16x32_bf16 v[32:35], v[194:197], v[226:229], v[32:35]
	v_mfma_f32_16x16x32_bf16 v[20:23], v[144:147], v[234:237], v[20:23]
	v_mfma_f32_16x16x32_bf16 v[16:19], v[194:197], v[234:237], v[16:19]
	v_mfma_f32_16x16x32_bf16 v[4:7], v[144:147], v[242:245], v[4:7]
	v_mfma_f32_16x16x32_bf16 v[0:3], v[194:197], v[242:245], v[0:3]
	v_mfma_f32_16x16x32_bf16 v[52:55], v[148:151], v[222:225], v[52:55]
	v_mfma_f32_16x16x32_bf16 v[48:51], v[202:205], v[222:225], v[48:51]
	v_mfma_f32_16x16x32_bf16 v[36:39], v[148:151], v[230:233], v[36:39]
	v_mfma_f32_16x16x32_bf16 v[32:35], v[202:205], v[230:233], v[32:35]
	v_mfma_f32_16x16x32_bf16 v[20:23], v[148:151], v[238:241], v[20:23]
	v_mfma_f32_16x16x32_bf16 v[16:19], v[202:205], v[238:241], v[16:19]
	v_mfma_f32_16x16x32_bf16 v[4:7], v[148:151], v[246:249], v[4:7]
	s_barrier
; #define PG8_STAGE(bufoff, gbase, voff) do { _Pragma("unroll") for (int _i = 0; _i < 2; ++_i) \
;         __builtin_amdgcn_global_load_lds((const unsigned*)((const char*)(gbase) + (voff)[_i]), (LAS unsigned*)(lds + (bufoff) + ldsw + _i * 8192), 16, 0, 0); } while (0)
; #define PG8_LDA(dst, b, h) do { _Pragma("unroll") for (int m = 0; m < 4; ++m) _Pragma("unroll") for (int k = 0; k < 2; ++k) dst[m][k] = *(const LAS bf16x8*)(lds + PG8_SA(b, h) + aoff + m * 2048 + k * 1024); } while (0)
; #define PG8_LDB(dst, b, h) do { _Pragma("unroll") for (int n = 0; n < 2; ++n) _Pragma("unroll") for (int k = 0; k < 2; ++k) dst[n][k] = *(const LAS bf16x8*)(lds + PG8_SB(b, h) + boff + n * 2048 + k * 1024); } while (0)
; #define PG8_MMA(ai, bj, At, Bt) do { __builtin_amdgcn_s_setprio(1); _Pragma("unroll") for (int m = 0; m < 4; ++m) _Pragma("unroll") for (int n = 0; n < 2; ++n) _Pragma("unroll") for (int k = 0; k < 2; ++k) \
;         acc[ai][bj][m][n] = __builtin_amdgcn_mfma_f32_16x16x32_bf16(Bt[n][k], At[m][k], acc[ai][bj][m][n], 0, 0, 0); __builtin_amdgcn_s_setprio(0); } while (0)
; #define PG8_WAIT_V(n) asm volatile("s_waitcnt vmcnt(" #n ")" ::: "memory")
; #define PG8_WAIT_L(n) asm volatile("s_waitcnt lgkmcnt(" #n ")" ::: "memory")
; #define PG8_BAR __builtin_amdgcn_s_barrier()
; #define PG8_SCHED __builtin_amdgcn_sched_barrier(0)
; template <class Epi, bool KREV = false>
; __device__ __forceinline__ void gemm_phase(LAS unsigned char* lds, const Gemm g, const StaticOrder& S, const Epi& E, int wave_s) {
;     ...
;             PG8_LDB(B0, 1, 0); PG8_LDB(B1, 1, 1); PG8_SCHED; PG8_LDA(At, 1, 0); PG8_STAGE(PG8_SA(0, 1), a2 + hstep, voffA);
;             PG8_WAIT_V(8); PG8_WAIT_L(0); PG8_BAR; PG8_MMA(0, 0, At, B0); PG8_MMA(0, 1, At, B1); PG8_BAR; PG8_SCHED;
;             PG8_LDA(At, 1, 1); PG8_STAGE(PG8_SB(1, 0), b3, voffB); PG8_STAGE(PG8_SB(1, 1), b3 + bh, voffB); PG8_STAGE(PG8_SA(1, 0), a3, voffA);
	v_mfma_f32_16x16x32_bf16 v[0:3], v[202:205], v[246:249], v[0:3]
	s_setprio 0
	s_add_i32 s23, 0, 0x18000
	s_add_i32 s45, 0, 0x1c000
	v_add_u32_e32 v140, s23, v199
	v_add_u32_e32 v202, s45, v199
	ds_read_b128 v[112:115], v140
	ds_read_b128 v[124:127], v140 offset:1024
	ds_read_b128 v[136:139], v140 offset:2048
	ds_read_b128 v[140:143], v140 offset:3072
	ds_read_b128 v[144:147], v202
	ds_read_b128 v[148:151], v202 offset:1024
	ds_read_b128 v[194:197], v202 offset:2048
	ds_read_b128 v[202:205], v202 offset:3072
	s_add_u32 s26, s26, 0x160000
	s_addc_u32 s27, s27, 0
	s_mov_b32 m0, s30
	ds_read_b128 v[218:221], v201 offset:32768
	ds_read_b128 v[222:225], v201 offset:33792
	ds_read_b128 v[226:229], v201 offset:34816
	ds_read_b128 v[230:233], v201 offset:35840
	ds_read_b128 v[234:237], v201 offset:36864
	ds_read_b128 v[238:241], v201 offset:37888
	ds_read_b128 v[242:245], v201 offset:38912
	ds_read_b128 v[246:249], v201 offset:39936
	global_load_lds_dwordx4 v156, s[26:27]
	s_mov_b32 m0, s34
	s_nop 0
	global_load_lds_dwordx4 v154, s[26:27]
	s_waitcnt vmcnt(8)
	s_waitcnt lgkmcnt(0)
	s_barrier
	s_setprio 1
	s_waitcnt lgkmcnt(0)
	v_mfma_f32_16x16x32_bf16 v[132:135], v[112:115], v[218:221], v[132:135]
	v_mfma_f32_16x16x32_bf16 v[120:123], v[136:139], v[218:221], v[120:123]
	v_mfma_f32_16x16x32_bf16 v[108:111], v[112:115], v[226:229], v[108:111]
	v_mfma_f32_16x16x32_bf16 v[104:107], v[136:139], v[226:229], v[104:107]
	v_mfma_f32_16x16x32_bf16 v[92:95], v[112:115], v[234:237], v[92:95]
	v_mfma_f32_16x16x32_bf16 v[88:91], v[136:139], v[234:237], v[88:91]
	v_mfma_f32_16x16x32_bf16 v[76:79], v[112:115], v[242:245], v[76:79]
	v_mfma_f32_16x16x32_bf16 v[72:75], v[136:139], v[242:245], v[72:75]
	v_mfma_f32_16x16x32_bf16 v[132:135], v[124:127], v[222:225], v[132:135]
	v_mfma_f32_16x16x32_bf16 v[120:123], v[140:143], v[222:225], v[120:123]
	v_mfma_f32_16x16x32_bf16 v[108:111], v[124:127], v[230:233], v[108:111]
	v_mfma_f32_16x16x32_bf16 v[104:107], v[140:143], v[230:233], v[104:107]
	v_mfma_f32_16x16x32_bf16 v[92:95], v[124:127], v[238:241], v[92:95]
	v_mfma_f32_16x16x32_bf16 v[88:91], v[140:143], v[238:241], v[88:91]
	v_mfma_f32_16x16x32_bf16 v[76:79], v[124:127], v[246:249], v[76:79]
	v_mfma_f32_16x16x32_bf16 v[72:75], v[140:143], v[246:249], v[72:75]
	s_setprio 0
	s_setprio 1
	v_mfma_f32_16x16x32_bf16 v[128:131], v[144:147], v[218:221], v[128:131]
	v_mfma_f32_16x16x32_bf16 v[116:119], v[194:197], v[218:221], v[116:119]
	v_mfma_f32_16x16x32_bf16 v[100:103], v[144:147], v[226:229], v[100:103]
	v_mfma_f32_16x16x32_bf16 v[96:99], v[194:197], v[226:229], v[96:99]
	v_mfma_f32_16x16x32_bf16 v[84:87], v[144:147], v[234:237], v[84:87]
	v_mfma_f32_16x16x32_bf16 v[80:83], v[194:197], v[234:237], v[80:83]
	v_mfma_f32_16x16x32_bf16 v[68:71], v[144:147], v[242:245], v[68:71]
	v_mfma_f32_16x16x32_bf16 v[64:67], v[194:197], v[242:245], v[64:67]
	v_mfma_f32_16x16x32_bf16 v[128:131], v[148:151], v[222:225], v[128:131]
	v_mfma_f32_16x16x32_bf16 v[116:119], v[202:205], v[222:225], v[116:119]
	v_mfma_f32_16x16x32_bf16 v[100:103], v[148:151], v[230:233], v[100:103]
	v_mfma_f32_16x16x32_bf16 v[96:99], v[202:205], v[230:233], v[96:99]
	v_mfma_f32_16x16x32_bf16 v[84:87], v[148:151], v[238:241], v[84:87]
	v_mfma_f32_16x16x32_bf16 v[80:83], v[202:205], v[238:241], v[80:83]
	v_mfma_f32_16x16x32_bf16 v[68:71], v[148:151], v[246:249], v[68:71]
	s_barrier
	v_mfma_f32_16x16x32_bf16 v[64:67], v[202:205], v[246:249], v[64:67]
	s_setprio 0
	s_add_i32 s23, s23, s1
	s_mov_b32 m0, s23
	ds_read_b128 v[218:221], v201 offset:49152
	ds_read_b128 v[222:225], v201 offset:50176
	ds_read_b128 v[226:229], v201 offset:51200
	ds_read_b128 v[230:233], v201 offset:52224
	ds_read_b128 v[234:237], v201 offset:53248
	ds_read_b128 v[238:241], v201 offset:54272
	ds_read_b128 v[242:245], v201 offset:55296
	ds_read_b128 v[246:249], v201 offset:56320
	global_load_lds_dwordx4 v176, s[98:99]
	s_add_i32 m0, s23, 0x2000
	s_add_u32 s24, s24, 0x15ff80
	s_addc_u32 s25, s25, 0
	s_add_i32 s23, s45, s1
	global_load_lds_dwordx4 v152, s[98:99]
	s_mov_b32 m0, s23
	s_nop 0
	global_load_lds_dwordx4 v176, s[24:25]
	s_add_i32 m0, s23, 0x2000
	s_nop 0
	global_load_lds_dwordx4 v152, s[24:25]
	s_mov_b32 m0, s36
	s_nop 0
	global_load_lds_dwordx4 v156, s[100:101]
	s_mov_b32 m0, s37
	s_nop 0
	global_load_lds_dwordx4 v154, s[100:101]
	s_waitcnt vmcnt(8)
	s_waitcnt lgkmcnt(0)
	s_barrier
; #define PG8_STAGE(bufoff, gbase, voff) do { _Pragma("unroll") for (int _i = 0; _i < 2; ++_i) \
;         __builtin_amdgcn_global_load_lds((const unsigned*)((const char*)(gbase) + (voff)[_i]), (LAS unsigned*)(lds + (bufoff) + ldsw + _i * 8192), 16, 0, 0); } while (0)
; #define PG8_LDA(dst, b, h) do { _Pragma("unroll") for (int m = 0; m < 4; ++m) _Pragma("unroll") for (int k = 0; k < 2; ++k) dst[m][k] = *(const LAS bf16x8*)(lds + PG8_SA(b, h) + aoff + m * 2048 + k * 1024); } while (0)
; #define PG8_LDB(dst, b, h) do { _Pragma("unroll") for (int n = 0; n < 2; ++n) _Pragma("unroll") for (int k = 0; k < 2; ++k) dst[n][k] = *(const LAS bf16x8*)(lds + PG8_SB(b, h) + boff + n * 2048 + k * 1024); } while (0)
; #define PG8_MMA(ai, bj, At, Bt) do { __builtin_amdgcn_s_setprio(1); _Pragma("unroll") for (int m = 0; m < 4; ++m) _Pragma("unroll") for (int n = 0; n < 2; ++n) _Pragma("unroll") for (int k = 0; k < 2; ++k) \
;         acc[ai][bj][m][n] = __builtin_amdgcn_mfma_f32_16x16x32_bf16(Bt[n][k], At[m][k], acc[ai][bj][m][n], 0, 0, 0); __builtin_amdgcn_s_setprio(0); } while (0)
; #define PG8_WAIT_V(n) asm volatile("s_waitcnt vmcnt(" #n ")" ::: "memory")
; #define PG8_WAIT_L(n) asm volatile("s_waitcnt lgkmcnt(" #n ")" ::: "memory")
; #define PG8_BAR __builtin_amdgcn_s_barrier()
; #define PG8_SCHED __builtin_amdgcn_sched_barrier(0)
; template <class Epi, bool KREV = false>
; __device__ __forceinline__ void gemm_phase(LAS unsigned char* lds, const Gemm g, const StaticOrder& S, const Epi& E, int wave_s) {
;     ...
;         const bool has_next = S.next(ui + 1, nxt);
;         const char* nA = has_next ? (const char*)g.A + (size_t)nxt.pm * tstep + k0off : cA; const char* nB = has_next ? (const char*)g.Bt + (size_t)nxt.pn * bunit + k0off : cB;
;         for (int t = 0; t < nt; t += 2) {
;             const bool last = (t == nt - 2);
;             const char* a1 = cA + (size_t)(t + 1) * kstep;
;             const char* a2 = last ? nA : cA + (size_t)(t + 2) * kstep; const char* b2 = last ? nB : cB + (size_t)(t + 2) * kstep;
;             const char* a3 = a2 + kstep; const char* b3 = b2 + kstep;
;             PG8_LDB(B0, 0, 0); PG8_LDB(B1, 0, 1); PG8_SCHED; PG8_LDA(At, 0, 0); PG8_STAGE(PG8_SA(1, 1), a1 + hstep, voffA);
;     ...
;             PG8_WAIT_V(8); PG8_WAIT_L(0); PG8_BAR; PG8_MMA(1, 0, At, B0); PG8_MMA(1, 1, At, B1); PG8_BAR; PG8_SCHED;
;         }
	s_setprio 1
	s_waitcnt lgkmcnt(0)
	v_mfma_f32_16x16x32_bf16 v[60:63], v[112:115], v[218:221], v[60:63]
	v_mfma_f32_16x16x32_bf16 v[56:59], v[136:139], v[218:221], v[56:59]
	v_mfma_f32_16x16x32_bf16 v[44:47], v[112:115], v[226:229], v[44:47]
	v_mfma_f32_16x16x32_bf16 v[40:43], v[136:139], v[226:229], v[40:43]
	v_mfma_f32_16x16x32_bf16 v[28:31], v[112:115], v[234:237], v[28:31]
	v_mfma_f32_16x16x32_bf16 v[24:27], v[136:139], v[234:237], v[24:27]
	v_mfma_f32_16x16x32_bf16 v[12:15], v[112:115], v[242:245], v[12:15]
	v_mfma_f32_16x16x32_bf16 v[8:11], v[136:139], v[242:245], v[8:11]
	v_mfma_f32_16x16x32_bf16 v[60:63], v[124:127], v[222:225], v[60:63]
	v_mfma_f32_16x16x32_bf16 v[56:59], v[140:143], v[222:225], v[56:59]
	v_mfma_f32_16x16x32_bf16 v[44:47], v[124:127], v[230:233], v[44:47]
	v_mfma_f32_16x16x32_bf16 v[40:43], v[140:143], v[230:233], v[40:43]
	v_mfma_f32_16x16x32_bf16 v[28:31], v[124:127], v[238:241], v[28:31]
	v_mfma_f32_16x16x32_bf16 v[24:27], v[140:143], v[238:241], v[24:27]
	v_mfma_f32_16x16x32_bf16 v[12:15], v[124:127], v[246:249], v[12:15]
	v_mfma_f32_16x16x32_bf16 v[8:11], v[140:143], v[246:249], v[8:11]
	s_setprio 0
	s_setprio 1
	v_mfma_f32_16x16x32_bf16 v[52:55], v[144:147], v[218:221], v[52:55]
	v_mfma_f32_16x16x32_bf16 v[48:51], v[194:197], v[218:221], v[48:51]
	v_mfma_f32_16x16x32_bf16 v[36:39], v[144:147], v[226:229], v[36:39]
	v_mfma_f32_16x16x32_bf16 v[32:35], v[194:197], v[226:229], v[32:35]
	v_mfma_f32_16x16x32_bf16 v[20:23], v[144:147], v[234:237], v[20:23]
	v_mfma_f32_16x16x32_bf16 v[16:19], v[194:197], v[234:237], v[16:19]
	v_mfma_f32_16x16x32_bf16 v[4:7], v[144:147], v[242:245], v[4:7]
	v_mfma_f32_16x16x32_bf16 v[0:3], v[194:197], v[242:245], v[0:3]
	s_cmpk_gt_u32 s44, 0x55
	s_cselect_b32 s32, 1, 0
	s_mov_b32 s44, s22
	v_mfma_f32_16x16x32_bf16 v[52:55], v[148:151], v[222:225], v[52:55]
	s_add_i32 s80, s44, 2
	s_lshl_b32 vcc_lo, s80, 7
	v_mfma_f32_16x16x32_bf16 v[48:51], v[202:205], v[222:225], v[48:51]
	s_sub_u32 s26, s18, vcc_lo
	s_subb_u32 s27, s19, 0
	v_mfma_f32_16x16x32_bf16 v[36:39], v[148:151], v[230:233], v[36:39]
	s_sub_u32 s24, s16, vcc_lo
	s_subb_u32 s25, s17, 0
	v_mfma_f32_16x16x32_bf16 v[32:35], v[202:205], v[230:233], v[32:35]
	s_cmp_eq_u32 s44, 0x56
	s_cselect_b32 s26, s20, s26
	s_cselect_b32 s27, s21, s27
	v_mfma_f32_16x16x32_bf16 v[20:23], v[148:151], v[238:241], v[20:23]
	s_cselect_b32 s24, s12, s24
	s_cselect_b32 s25, s13, s25
	s_cselect_b32 s22, 0x58, s80
	v_mfma_f32_16x16x32_bf16 v[16:19], v[202:205], v[238:241], v[16:19]
	s_cmp_lg_u32 s32, 0
	v_mfma_f32_16x16x32_bf16 v[4:7], v[148:151], v[246:249], v[4:7]
	s_barrier
	v_mfma_f32_16x16x32_bf16 v[0:3], v[202:205], v[246:249], v[0:3]
	s_setprio 0
	s_cbranch_scc1 .LBB0_1028
	v_add_u32_e32 v140, 0x10000, v199
	v_add_u32_e32 v202, 0x14000, v199
	ds_read_b128 v[112:115], v140
	ds_read_b128 v[124:127], v140 offset:1024
	ds_read_b128 v[136:139], v140 offset:2048
	ds_read_b128 v[140:143], v140 offset:3072
	ds_read_b128 v[144:147], v202
	ds_read_b128 v[148:151], v202 offset:1024
	ds_read_b128 v[194:197], v202 offset:2048
	ds_read_b128 v[202:205], v202 offset:3072
	ds_read_b128 v[218:221], v201
	ds_read_b128 v[222:225], v201 offset:1024
	ds_read_b128 v[226:229], v201 offset:2048
	ds_read_b128 v[230:233], v201 offset:3072
	ds_read_b128 v[234:237], v201 offset:4096
	ds_read_b128 v[238:241], v201 offset:5120
	ds_read_b128 v[242:245], v201 offset:6144
	ds_read_b128 v[246:249], v201 offset:7168
	s_branch .LBB0_1023
